# cross-attention tile loop: one static s_setprio 1 for waves 4-7 (reset after the loop)
# speedup vs baseline: 1.0046x; 1.0046x over previous
; __device__ __forceinline__ void xattn_phase(const bf16* QXB, const bf16* MKF, const bf16* MVF, bf16* OXB, int G, int tid) {
;     ...
;     for (int it = (int)blockIdx.x * (MK_THREADS / 64) + wave; it < NIT; it += G * (MK_THREADS / 64)) { const int qb = it % NQ32, bhx = it / NQ32, h = bhx % XH, b = bhx / XH;
;         const size_t row0 = (size_t)b * SEQ + 32 * qb;
;         const bf16* qp = QXB + (row0 + r32) * XW + h * XHD + 8 * hh; const bf16* kp = MKF + (size_t)(b * XH + h) * 32768 + lane * 8;
;         bf16x8 qf[8];
; #pragma unroll
;         for (int ks = 0; ks < 8; ++ks) qf[ks] = *(const bf16x8*)(qp + 16 * ks);
;         const bf16* vp = MVF + (size_t)(b * XH + h) * 32768 + lane * 16;
;         f32x16 o[4]; o[0] = f32x16{}; o[1] = f32x16{}; o[2] = f32x16{}; o[3] = f32x16{}; float m_run = -INFINITY, l_run = 0.f;
;     ...
;         bf16x8 kfa[8], kfb[8];
; #pragma unroll
;         for (int ks = 0; ks < 8; ++ks) kfa[ks] = *(const bf16x8*)(kp + ks * 512);
.LBB0_1511:
	s_ashr_i32 s0, s8, 31
	s_lshr_b32 s1, s0, 25
	s_add_i32 s1, s8, s1
	s_ashr_i32 s2, s1, 7
	s_and_b32 s1, s1, 0x7ffff80
	s_sub_i32 s6, s8, s1
	s_lshr_b32 s1, s2, 30
	s_add_i32 s1, s2, s1
	s_lshr_b32 s0, s0, 23
	s_and_b32 s1, s1, -4
	s_add_i32 s0, s8, s0
	s_sub_i32 s7, s2, s1
	s_ashr_i32 s2, s0, 9
	s_ashr_i32 s3, s2, 31
	s_lshl_b64 s[0:1], s[2:3], 12
	s_lshl_b32 s3, s6, 5
	s_ashr_i32 s6, s3, 31
	s_add_u32 s0, s0, s3
	s_addc_u32 s1, s1, s6
	v_mov_b32_e32 v3, s1
	v_or_b32_e32 v2, s0, v222
	v_readlane_b32 s0, v252, 19
	v_lshlrev_b64 v[4:5], 10, v[2:3]
	v_readlane_b32 s1, v252, 20
	s_lshl_b32 s2, s2, 2
	s_add_i32 s2, s2, s7
	v_lshl_add_u64 v[4:5], s[0:1], 0, v[4:5]
	s_lshl_b32 s0, s7, 7
	s_ashr_i32 s1, s0, 31
	v_lshl_add_u64 v[4:5], s[0:1], 1, v[4:5]
	v_lshl_add_u64 v[4:5], v[4:5], 0, v[214:215]
	s_ashr_i32 s3, s2, 31
	global_load_dwordx4 v[82:85], v[4:5], off
	global_load_dwordx4 v[86:89], v[4:5], off offset:32
	global_load_dwordx4 v[90:93], v[4:5], off offset:64
	global_load_dwordx4 v[94:97], v[4:5], off offset:96
	global_load_dwordx4 v[98:101], v[4:5], off offset:128
	global_load_dwordx4 v[102:105], v[4:5], off offset:160
	global_load_dwordx4 v[106:109], v[4:5], off offset:192
	global_load_dwordx4 v[110:113], v[4:5], off offset:224
	s_lshl_b64 s[2:3], s[2:3], 16
	v_lshl_add_u64 v[182:183], v[226:227], 0, s[2:3]
	v_mov_b32_e32 v50, v215
	v_mov_b32_e32 v51, v215
	v_lshlrev_b64 v[232:233], 9, v[2:3]
	s_add_u32 s2, s9, s2
	v_mov_b32_e32 v52, v215
	v_mov_b32_e32 v53, v215
	v_mov_b32_e32 v54, v215
	v_mov_b32_e32 v55, v215
	v_mov_b32_e32 v56, v215
	v_mov_b32_e32 v57, v215
	v_mov_b32_e32 v58, v215
	v_mov_b32_e32 v59, v215
	v_mov_b32_e32 v60, v215
	v_mov_b32_e32 v61, v215
	v_mov_b32_e32 v62, v215
	v_mov_b32_e32 v63, v215
	v_mov_b32_e32 v64, v215
	v_mov_b32_e32 v65, v215
	v_mov_b64_e32 v[34:35], v[50:51]
	v_mov_b64_e32 v[18:19], v[50:51]
	v_mov_b64_e32 v[2:3], v[50:51]
	s_mov_b32 s11, 0
	s_addc_u32 s3, s10, s3
	v_mov_b32_e32 v231, 0
	v_mov_b32_e32 v248, 0xff800000
	v_mov_b64_e32 v[36:37], v[52:53]
	v_mov_b64_e32 v[38:39], v[54:55]
	v_mov_b64_e32 v[40:41], v[56:57]
	v_mov_b64_e32 v[42:43], v[58:59]
	v_mov_b64_e32 v[44:45], v[60:61]
	v_mov_b64_e32 v[46:47], v[62:63]
	v_mov_b64_e32 v[48:49], v[64:65]
	v_mov_b64_e32 v[20:21], v[52:53]
	v_mov_b64_e32 v[22:23], v[54:55]
	v_mov_b64_e32 v[24:25], v[56:57]
	v_mov_b64_e32 v[26:27], v[58:59]
	v_mov_b64_e32 v[28:29], v[60:61]
	v_mov_b64_e32 v[30:31], v[62:63]
	v_mov_b64_e32 v[32:33], v[64:65]
	v_mov_b64_e32 v[4:5], v[52:53]
	v_mov_b64_e32 v[6:7], v[54:55]
	v_mov_b64_e32 v[8:9], v[56:57]
	v_mov_b64_e32 v[10:11], v[58:59]
	v_mov_b64_e32 v[12:13], v[60:61]
	v_mov_b64_e32 v[14:15], v[62:63]
	v_mov_b64_e32 v[16:17], v[64:65]
	s_and_b32 s6, s8, 7
	s_lshl_b32 s6, s6, 13
	s_mov_b32 s7, 0
	v_lshl_add_u64 v[182:183], s[6:7], 0, v[182:183]
	global_load_dwordx4 v[114:117], v[182:183], off
	global_load_dwordx4 v[118:121], v[182:183], off offset:1024
	global_load_dwordx4 v[122:125], v[182:183], off offset:2048
	global_load_dwordx4 v[126:129], v[182:183], off offset:3072
	v_add_co_u32_e32 v184, vcc, 0x1000, v182
	s_nop 1
	v_addc_co_u32_e32 v185, vcc, 0, v183, vcc
	global_load_dwordx4 v[130:133], v[184:185], off
	global_load_dwordx4 v[134:137], v[184:185], off offset:1024
	global_load_dwordx4 v[138:141], v[184:185], off offset:2048
	global_load_dwordx4 v[142:145], v[184:185], off offset:3072
	v_lshl_add_u64 v[186:187], s[6:7], 0, v[228:229]
	v_lshl_add_u64 v[186:187], s[2:3], 0, v[186:187]
	v_add_co_u32_e32 v186, vcc, 0x22a00000, v186
	s_nop 1
	v_addc_co_u32_e32 v187, vcc, 0, v187, vcc
	v_add_co_u32_e32 v184, vcc, 0x1000, v186
	s_nop 1
	v_addc_co_u32_e32 v185, vcc, 0, v187, vcc
	global_load_dwordx4 v[146:149], v[186:187], off
	global_load_dwordx4 v[162:165], v[186:187], off offset:16
	global_load_dwordx4 v[150:153], v[186:187], off offset:2048
	global_load_dwordx4 v[166:169], v[186:187], off offset:2064
	global_load_dwordx4 v[154:157], v[184:185], off
	global_load_dwordx4 v[170:173], v[184:185], off offset:16
	global_load_dwordx4 v[158:161], v[184:185], off offset:2048
	global_load_dwordx4 v[174:177], v[184:185], off offset:2064
	v_add_u32_e32 v188, s6, v224
	v_add_u32_e32 v189, 0x10000, v188
	s_waitcnt vmcnt(0)
	ds_write_b128 v188, v[114:117]
	ds_write_b128 v188, v[118:121] offset:1024
	ds_write_b128 v188, v[122:125] offset:2048
	ds_write_b128 v188, v[126:129] offset:3072
	ds_write_b128 v188, v[130:133] offset:4096
	ds_write_b128 v188, v[134:137] offset:5120
	ds_write_b128 v188, v[138:141] offset:6144
	ds_write_b128 v188, v[142:145] offset:7168
	ds_write_b128 v189, v[146:149]
	ds_write_b128 v189, v[162:165] offset:1024
	ds_write_b128 v189, v[150:153] offset:2048
	ds_write_b128 v189, v[166:169] offset:3072
	ds_write_b128 v189, v[154:157] offset:4096
	ds_write_b128 v189, v[170:173] offset:5120
	ds_write_b128 v189, v[158:161] offset:6144
	ds_write_b128 v189, v[174:177] offset:7168
	v_mov_b32_e32 v180, v224
	v_add_u32_e32 v181, 0x10000, v224
	s_waitcnt lgkmcnt(0)
	s_barrier
	s_cmp_lt_u32 s6, 0x8000
	s_cbranch_scc1 .Lxa_np
	s_setprio 1
.Lxa_np:
	ds_read_b128 v[114:117], v180
	ds_read_b128 v[118:121], v180 offset:1024
	ds_read_b128 v[122:125], v180 offset:2048
	ds_read_b128 v[126:129], v180 offset:3072
	ds_read_b128 v[130:133], v180 offset:4096
	ds_read_b128 v[134:137], v180 offset:5120
	ds_read_b128 v[138:141], v180 offset:6144
	ds_read_b128 v[142:145], v180 offset:7168

; __device__ __forceinline__ void xattn_phase(const bf16* QXB, const bf16* MKF, const bf16* MVF, bf16* OXB, int G, int tid) {
;     ...
;         bf16x8 kfa[8], kfb[8];
; #pragma unroll
;         for (int ks = 0; ks < 8; ++ks) kfa[ks] = *(const bf16x8*)(kp + ks * 512);
; #pragma unroll 1
;         for (int kt = 0; kt < 8; kt += 2) { XA_TILE(kt, kfa, kfb, true) XA_TILE(kt + 1, kfb, kfa, kt + 2 < 8) }
.Lxa_noresc:
	v_add_f32_e32 v221, v221, v238
	v_fmac_f32_e32 v221, v231, v236
	s_nop 0
	v_mov_b32_e32 v231, v221
	v_cvt_pk_bf16_f32 v66, v66, v67
	v_cvt_pk_bf16_f32 v67, v68, v69
	v_cvt_pk_bf16_f32 v68, v70, v71
	v_cvt_pk_bf16_f32 v69, v72, v73
	v_cvt_pk_bf16_f32 v70, v74, v75
	v_cvt_pk_bf16_f32 v71, v76, v77
	v_cvt_pk_bf16_f32 v72, v78, v79
	v_cvt_pk_bf16_f32 v73, v80, v81
	s_nop 1
	v_mfma_f32_32x32x16_bf16 v[50:65], v[146:149], v[66:69], v[50:65]
	v_mfma_f32_32x32x16_bf16 v[34:49], v[150:153], v[66:69], v[34:49]
	v_mfma_f32_32x32x16_bf16 v[18:33], v[154:157], v[66:69], v[18:33]
	v_mfma_f32_32x32x16_bf16 v[2:17], v[158:161], v[66:69], v[2:17]
	v_mfma_f32_32x32x16_bf16 v[50:65], v[162:165], v[70:73], v[50:65]
	v_mfma_f32_32x32x16_bf16 v[34:49], v[166:169], v[70:73], v[34:49]
	v_mfma_f32_32x32x16_bf16 v[18:33], v[170:173], v[70:73], v[18:33]
	v_mfma_f32_32x32x16_bf16 v[2:17], v[174:177], v[70:73], v[2:17]
	v_add_u32_e32 v181, 0x2000, v181
	s_add_i32 s11, s11, 1
	s_cmp_lt_u32 s11, 8
	s_cbranch_scc1 .Lxa_tile
	s_waitcnt lgkmcnt(0)
	s_setprio 0
	s_nop 15
	s_branch .LBB0_1510
